# 9 GEMM K-loop heads aligned to 64 bytes (.p2align 6, s_nop padding executed once per unit)
# speedup vs baseline: 1.0088x; 1.0016x over previous
.LBB0_181:
	s_ashr_i32 s13, s12, 31
	s_lshl_b64 s[14:15], s[12:13], 21
	v_readlane_b32 s30, v253, 6
	v_readlane_b32 s31, v253, 7
	s_add_u32 s14, s30, s14
	s_addc_u32 s15, s31, s15
	s_and_b64 s[30:31], s[0:1], exec
	s_cselect_b32 s13, s15, s73
	s_cselect_b32 s37, s14, s72
	s_ashr_i32 s11, s10, 31
	s_lshl_b64 s[30:31], s[10:11], 21
	s_add_u32 s34, s16, s30
	s_addc_u32 s35, s17, s31
	s_and_b64 s[30:31], s[0:1], exec
	s_cselect_b32 s11, s35, s75
	s_cselect_b32 s38, s34, s74
	s_add_u32 s72, s72, 0x100080
	s_addc_u32 s73, s73, 0
	s_add_u32 s39, s74, 0x100
	v_mov_b32_e32 v0, 0
	s_addc_u32 s40, s75, 0
	s_mov_b32 s41, -2
	v_mov_b32_e32 v1, v0
	v_mov_b32_e32 v2, v0
	v_mov_b32_e32 v3, v0
	v_mov_b32_e32 v4, v0
	v_mov_b32_e32 v5, v0
	v_mov_b32_e32 v6, v0
	v_mov_b32_e32 v7, v0
	v_mov_b32_e32 v16, v0
	v_mov_b32_e32 v17, v0
	v_mov_b32_e32 v18, v0
	v_mov_b32_e32 v19, v0
	v_mov_b32_e32 v20, v0
	v_mov_b32_e32 v21, v0
	v_mov_b32_e32 v22, v0
	v_mov_b32_e32 v23, v0
	v_mov_b32_e32 v32, v0
	v_mov_b32_e32 v33, v0
	v_mov_b32_e32 v34, v0
	v_mov_b32_e32 v35, v0
	v_mov_b32_e32 v36, v0
	v_mov_b32_e32 v37, v0
	v_mov_b32_e32 v38, v0
	v_mov_b32_e32 v39, v0
	v_mov_b32_e32 v48, v0
	v_mov_b32_e32 v49, v0
	v_mov_b32_e32 v50, v0
	v_mov_b32_e32 v51, v0
	v_mov_b32_e32 v52, v0
	v_mov_b32_e32 v53, v0
	v_mov_b32_e32 v54, v0
	v_mov_b32_e32 v55, v0
	v_mov_b32_e32 v8, v0
	v_mov_b32_e32 v9, v0
	v_mov_b32_e32 v10, v0
	v_mov_b32_e32 v11, v0
	v_mov_b32_e32 v12, v0
	v_mov_b32_e32 v13, v0
	v_mov_b32_e32 v14, v0
	v_mov_b32_e32 v15, v0
	v_mov_b32_e32 v24, v0
	v_mov_b32_e32 v25, v0
	v_mov_b32_e32 v26, v0
	v_mov_b32_e32 v27, v0
	v_mov_b32_e32 v28, v0
	v_mov_b32_e32 v29, v0
	v_mov_b32_e32 v30, v0
	v_mov_b32_e32 v31, v0
	v_mov_b32_e32 v40, v0
	v_mov_b32_e32 v41, v0
	v_mov_b32_e32 v42, v0
	v_mov_b32_e32 v43, v0
	v_mov_b32_e32 v44, v0
	v_mov_b32_e32 v45, v0
	v_mov_b32_e32 v46, v0
	v_mov_b32_e32 v47, v0
	v_mov_b32_e32 v56, v0
	v_mov_b32_e32 v57, v0
	v_mov_b32_e32 v58, v0
	v_mov_b32_e32 v59, v0
	v_mov_b32_e32 v60, v0
	v_mov_b32_e32 v61, v0
	v_mov_b32_e32 v62, v0
	v_mov_b32_e32 v63, v0
	v_mov_b32_e32 v64, v0
	v_mov_b32_e32 v65, v0
	v_mov_b32_e32 v66, v0
	v_mov_b32_e32 v67, v0
	v_mov_b32_e32 v68, v0
	v_mov_b32_e32 v69, v0
	v_mov_b32_e32 v70, v0
	v_mov_b32_e32 v71, v0
	v_mov_b32_e32 v80, v0
	v_mov_b32_e32 v81, v0
	v_mov_b32_e32 v82, v0
	v_mov_b32_e32 v83, v0
	v_mov_b32_e32 v84, v0
	v_mov_b32_e32 v85, v0
	v_mov_b32_e32 v86, v0
	v_mov_b32_e32 v87, v0
	v_mov_b32_e32 v96, v0
	v_mov_b32_e32 v97, v0
	v_mov_b32_e32 v98, v0
	v_mov_b32_e32 v99, v0
	v_mov_b32_e32 v100, v0
	v_mov_b32_e32 v101, v0
	v_mov_b32_e32 v102, v0
	v_mov_b32_e32 v103, v0
	v_mov_b32_e32 v112, v0
	v_mov_b32_e32 v113, v0
	v_mov_b32_e32 v114, v0
	v_mov_b32_e32 v115, v0
	v_mov_b32_e32 v116, v0
	v_mov_b32_e32 v117, v0
	v_mov_b32_e32 v118, v0
	v_mov_b32_e32 v119, v0
	v_mov_b32_e32 v72, v0
	v_mov_b32_e32 v73, v0
	v_mov_b32_e32 v74, v0
	v_mov_b32_e32 v75, v0
	v_mov_b32_e32 v76, v0
	v_mov_b32_e32 v77, v0
	v_mov_b32_e32 v78, v0
	v_mov_b32_e32 v79, v0
	v_mov_b32_e32 v88, v0
	v_mov_b32_e32 v89, v0
	v_mov_b32_e32 v90, v0
	v_mov_b32_e32 v91, v0
	v_mov_b32_e32 v92, v0
	v_mov_b32_e32 v93, v0
	v_mov_b32_e32 v94, v0
	v_mov_b32_e32 v95, v0
	v_mov_b32_e32 v104, v0
	v_mov_b32_e32 v105, v0
	v_mov_b32_e32 v106, v0
	v_mov_b32_e32 v107, v0
	v_mov_b32_e32 v108, v0
	v_mov_b32_e32 v109, v0
	v_mov_b32_e32 v110, v0
	v_mov_b32_e32 v111, v0
	v_mov_b32_e32 v120, v0
	v_mov_b32_e32 v121, v0
	v_mov_b32_e32 v122, v0
	v_mov_b32_e32 v123, v0
	v_mov_b32_e32 v124, v0
	v_mov_b32_e32 v125, v0
	v_mov_b32_e32 v126, v0
	v_mov_b32_e32 v127, v0
	.p2align	6

.LBB0_400:
	s_add_i32 s17, s87, -2
	s_add_u32 s36, s46, 0x100
	v_mov_b32_e32 v0, 0
	s_addc_u32 s37, s47, 0
	s_mov_b32 s30, 0
	v_mov_b32_e32 v1, v0
	v_mov_b32_e32 v2, v0
	v_mov_b32_e32 v3, v0
	v_mov_b32_e32 v4, v0
	v_mov_b32_e32 v5, v0
	v_mov_b32_e32 v6, v0
	v_mov_b32_e32 v7, v0
	v_mov_b32_e32 v16, v0
	v_mov_b32_e32 v17, v0
	v_mov_b32_e32 v18, v0
	v_mov_b32_e32 v19, v0
	v_mov_b32_e32 v20, v0
	v_mov_b32_e32 v21, v0
	v_mov_b32_e32 v22, v0
	v_mov_b32_e32 v23, v0
	v_mov_b32_e32 v32, v0
	v_mov_b32_e32 v33, v0
	v_mov_b32_e32 v34, v0
	v_mov_b32_e32 v35, v0
	v_mov_b32_e32 v36, v0
	v_mov_b32_e32 v37, v0
	v_mov_b32_e32 v38, v0
	v_mov_b32_e32 v39, v0
	v_mov_b32_e32 v48, v0
	v_mov_b32_e32 v49, v0
	v_mov_b32_e32 v50, v0
	v_mov_b32_e32 v51, v0
	v_mov_b32_e32 v52, v0
	v_mov_b32_e32 v53, v0
	v_mov_b32_e32 v54, v0
	v_mov_b32_e32 v55, v0
	v_mov_b32_e32 v8, v0
	v_mov_b32_e32 v9, v0
	v_mov_b32_e32 v10, v0
	v_mov_b32_e32 v11, v0
	v_mov_b32_e32 v12, v0
	v_mov_b32_e32 v13, v0
	v_mov_b32_e32 v14, v0
	v_mov_b32_e32 v15, v0
	v_mov_b32_e32 v24, v0
	v_mov_b32_e32 v25, v0
	v_mov_b32_e32 v26, v0
	v_mov_b32_e32 v27, v0
	v_mov_b32_e32 v28, v0
	v_mov_b32_e32 v29, v0
	v_mov_b32_e32 v30, v0
	v_mov_b32_e32 v31, v0
	v_mov_b32_e32 v40, v0
	v_mov_b32_e32 v41, v0
	v_mov_b32_e32 v42, v0
	v_mov_b32_e32 v43, v0
	v_mov_b32_e32 v44, v0
	v_mov_b32_e32 v45, v0
	v_mov_b32_e32 v46, v0
	v_mov_b32_e32 v47, v0
	v_mov_b32_e32 v56, v0
	v_mov_b32_e32 v57, v0
	v_mov_b32_e32 v58, v0
	v_mov_b32_e32 v59, v0
	v_mov_b32_e32 v60, v0
	v_mov_b32_e32 v61, v0
	v_mov_b32_e32 v62, v0
	v_mov_b32_e32 v63, v0
	v_mov_b32_e32 v64, v0
	v_mov_b32_e32 v65, v0
	v_mov_b32_e32 v66, v0
	v_mov_b32_e32 v67, v0
	v_mov_b32_e32 v68, v0
	v_mov_b32_e32 v69, v0
	v_mov_b32_e32 v70, v0
	v_mov_b32_e32 v71, v0
	v_mov_b32_e32 v80, v0
	v_mov_b32_e32 v81, v0
	v_mov_b32_e32 v82, v0
	v_mov_b32_e32 v83, v0
	v_mov_b32_e32 v84, v0
	v_mov_b32_e32 v85, v0
	v_mov_b32_e32 v86, v0
	v_mov_b32_e32 v87, v0
	v_mov_b32_e32 v96, v0
	v_mov_b32_e32 v97, v0
	v_mov_b32_e32 v98, v0
	v_mov_b32_e32 v99, v0
	v_mov_b32_e32 v100, v0
	v_mov_b32_e32 v101, v0
	v_mov_b32_e32 v102, v0
	v_mov_b32_e32 v103, v0
	v_mov_b32_e32 v112, v0
	v_mov_b32_e32 v113, v0
	v_mov_b32_e32 v114, v0
	v_mov_b32_e32 v115, v0
	v_mov_b32_e32 v116, v0
	v_mov_b32_e32 v117, v0
	v_mov_b32_e32 v118, v0
	v_mov_b32_e32 v119, v0
	v_mov_b32_e32 v72, v0
	v_mov_b32_e32 v73, v0
	v_mov_b32_e32 v74, v0
	v_mov_b32_e32 v75, v0
	v_mov_b32_e32 v76, v0
	v_mov_b32_e32 v77, v0
	v_mov_b32_e32 v78, v0
	v_mov_b32_e32 v79, v0
	v_mov_b32_e32 v88, v0
	v_mov_b32_e32 v89, v0
	v_mov_b32_e32 v90, v0
	v_mov_b32_e32 v91, v0
	v_mov_b32_e32 v92, v0
	v_mov_b32_e32 v93, v0
	v_mov_b32_e32 v94, v0
	v_mov_b32_e32 v95, v0
	v_mov_b32_e32 v104, v0
	v_mov_b32_e32 v105, v0
	v_mov_b32_e32 v106, v0
	v_mov_b32_e32 v107, v0
	v_mov_b32_e32 v108, v0
	v_mov_b32_e32 v109, v0
	v_mov_b32_e32 v110, v0
	v_mov_b32_e32 v111, v0
	v_mov_b32_e32 v120, v0
	v_mov_b32_e32 v121, v0
	v_mov_b32_e32 v122, v0
	v_mov_b32_e32 v123, v0
	v_mov_b32_e32 v124, v0
	v_mov_b32_e32 v125, v0
	v_mov_b32_e32 v126, v0
	v_mov_b32_e32 v127, v0
	.p2align	6

.LBB0_574:
	s_ashr_i32 s17, s16, 31
	s_lshl_b64 s[30:31], s[16:17], 21
	v_readlane_b32 s38, v253, 6
	v_readlane_b32 s39, v253, 7
	s_add_u32 s7, s38, s30
	s_addc_u32 s17, s39, s31
	s_ashr_i32 s15, s14, 31
	s_lshl_b64 s[30:31], s[14:15], 7
	s_add_u32 s44, s7, s30
	s_addc_u32 s45, s17, s31
	s_ashr_i32 s35, s34, 31
	s_lshl_b64 s[38:39], s[34:35], 21
	s_add_u32 s7, s56, s38
	s_addc_u32 s15, s57, s39
	s_add_u32 s46, s7, s30
	s_addc_u32 s47, s15, s31
	s_cmp_lt_i32 s36, 1
	s_cbranch_scc1 .LBB0_580
	s_and_b64 s[30:31], s[40:41], exec
	s_cselect_b32 s7, s45, s53
	s_cselect_b32 s15, s44, s52
	s_cselect_b32 s17, s47, s55
	s_cselect_b32 s35, s46, s54
	s_add_i32 s37, s36, -2
	s_add_u32 s52, s52, 0x100080
	s_addc_u32 s53, s53, 0
	s_add_u32 s38, s54, 0x100
	v_mov_b32_e32 v64, 0
	s_addc_u32 s39, s55, 0
	s_mov_b32 s30, 0
	v_mov_b32_e32 v65, v64
	v_mov_b32_e32 v66, v64
	v_mov_b32_e32 v67, v64
	v_mov_b32_e32 v68, v64
	v_mov_b32_e32 v69, v64
	v_mov_b32_e32 v70, v64
	v_mov_b32_e32 v71, v64
	v_mov_b32_e32 v72, v64
	v_mov_b32_e32 v73, v64
	v_mov_b32_e32 v74, v64
	v_mov_b32_e32 v75, v64
	v_mov_b32_e32 v76, v64
	v_mov_b32_e32 v77, v64
	v_mov_b32_e32 v78, v64
	v_mov_b32_e32 v79, v64
	v_mov_b32_e32 v80, v64
	v_mov_b32_e32 v81, v64
	v_mov_b32_e32 v82, v64
	v_mov_b32_e32 v83, v64
	v_mov_b32_e32 v84, v64
	v_mov_b32_e32 v85, v64
	v_mov_b32_e32 v86, v64
	v_mov_b32_e32 v87, v64
	v_mov_b32_e32 v88, v64
	v_mov_b32_e32 v89, v64
	v_mov_b32_e32 v90, v64
	v_mov_b32_e32 v91, v64
	v_mov_b32_e32 v92, v64
	v_mov_b32_e32 v93, v64
	v_mov_b32_e32 v94, v64
	v_mov_b32_e32 v95, v64
	v_mov_b32_e32 v0, v64
	v_mov_b32_e32 v1, v64
	v_mov_b32_e32 v2, v64
	v_mov_b32_e32 v3, v64
	v_mov_b32_e32 v4, v64
	v_mov_b32_e32 v5, v64
	v_mov_b32_e32 v6, v64
	v_mov_b32_e32 v7, v64
	v_mov_b32_e32 v8, v64
	v_mov_b32_e32 v9, v64
	v_mov_b32_e32 v10, v64
	v_mov_b32_e32 v11, v64
	v_mov_b32_e32 v12, v64
	v_mov_b32_e32 v13, v64
	v_mov_b32_e32 v14, v64
	v_mov_b32_e32 v15, v64
	v_mov_b32_e32 v16, v64
	v_mov_b32_e32 v17, v64
	v_mov_b32_e32 v18, v64
	v_mov_b32_e32 v19, v64
	v_mov_b32_e32 v20, v64
	v_mov_b32_e32 v21, v64
	v_mov_b32_e32 v22, v64
	v_mov_b32_e32 v23, v64
	v_mov_b32_e32 v24, v64
	v_mov_b32_e32 v25, v64
	v_mov_b32_e32 v26, v64
	v_mov_b32_e32 v27, v64
	v_mov_b32_e32 v28, v64
	v_mov_b32_e32 v29, v64
	v_mov_b32_e32 v30, v64
	v_mov_b32_e32 v31, v64
	v_mov_b32_e32 v96, v64
	v_mov_b32_e32 v97, v64
	v_mov_b32_e32 v98, v64
	v_mov_b32_e32 v99, v64
	v_mov_b32_e32 v100, v64
	v_mov_b32_e32 v101, v64
	v_mov_b32_e32 v102, v64
	v_mov_b32_e32 v103, v64
	v_mov_b32_e32 v104, v64
	v_mov_b32_e32 v105, v64
	v_mov_b32_e32 v106, v64
	v_mov_b32_e32 v107, v64
	v_mov_b32_e32 v108, v64
	v_mov_b32_e32 v109, v64
	v_mov_b32_e32 v110, v64
	v_mov_b32_e32 v111, v64
	v_mov_b32_e32 v112, v64
	v_mov_b32_e32 v113, v64
	v_mov_b32_e32 v114, v64
	v_mov_b32_e32 v115, v64
	v_mov_b32_e32 v116, v64
	v_mov_b32_e32 v117, v64
	v_mov_b32_e32 v118, v64
	v_mov_b32_e32 v119, v64
	v_mov_b32_e32 v120, v64
	v_mov_b32_e32 v121, v64
	v_mov_b32_e32 v122, v64
	v_mov_b32_e32 v123, v64
	v_mov_b32_e32 v124, v64
	v_mov_b32_e32 v125, v64
	v_mov_b32_e32 v126, v64
	v_mov_b32_e32 v127, v64
	v_mov_b32_e32 v32, v64
	v_mov_b32_e32 v33, v64
	v_mov_b32_e32 v34, v64
	v_mov_b32_e32 v35, v64
	v_mov_b32_e32 v36, v64
	v_mov_b32_e32 v37, v64
	v_mov_b32_e32 v38, v64
	v_mov_b32_e32 v39, v64
	v_mov_b32_e32 v40, v64
	v_mov_b32_e32 v41, v64
	v_mov_b32_e32 v42, v64
	v_mov_b32_e32 v43, v64
	v_mov_b32_e32 v44, v64
	v_mov_b32_e32 v45, v64
	v_mov_b32_e32 v46, v64
	v_mov_b32_e32 v47, v64
	v_mov_b32_e32 v48, v64
	v_mov_b32_e32 v49, v64
	v_mov_b32_e32 v50, v64
	v_mov_b32_e32 v51, v64
	v_mov_b32_e32 v52, v64
	v_mov_b32_e32 v53, v64
	v_mov_b32_e32 v54, v64
	v_mov_b32_e32 v55, v64
	v_mov_b32_e32 v56, v64
	v_mov_b32_e32 v57, v64
	v_mov_b32_e32 v58, v64
	v_mov_b32_e32 v59, v64
	v_mov_b32_e32 v60, v64
	v_mov_b32_e32 v61, v64
	v_mov_b32_e32 v62, v64
	v_mov_b32_e32 v63, v64
	.p2align	6

.LBB0_737:
	s_ashr_i32 s39, s38, 31
	s_lshl_b64 s[30:31], s[38:39], 19
	s_add_u32 s40, s33, s30
	s_addc_u32 s41, s52, s31
	s_and_b64 s[30:31], s[0:1], exec
	s_cselect_b32 s36, s41, s45
	s_cselect_b32 s37, s40, s44
	s_ashr_i32 s35, s34, 31
	s_lshl_b64 s[30:31], s[34:35], 19
	s_add_u32 s42, s28, s30
	s_addc_u32 s43, s29, s31
	s_and_b64 s[30:31], s[0:1], exec
	s_cselect_b32 s35, s43, s47
	s_cselect_b32 s39, s42, s46
	s_add_u32 s44, s44, 0x40080
	s_addc_u32 s45, s45, 0
	s_add_u32 s48, s46, 0x100
	v_mov_b32_e32 v0, 0
	s_addc_u32 s49, s47, 0
	s_mov_b32 s50, -2
	v_mov_b32_e32 v1, v0
	v_mov_b32_e32 v2, v0
	v_mov_b32_e32 v3, v0
	v_mov_b32_e32 v4, v0
	v_mov_b32_e32 v5, v0
	v_mov_b32_e32 v6, v0
	v_mov_b32_e32 v7, v0
	v_mov_b32_e32 v8, v0
	v_mov_b32_e32 v9, v0
	v_mov_b32_e32 v10, v0
	v_mov_b32_e32 v11, v0
	v_mov_b32_e32 v16, v0
	v_mov_b32_e32 v17, v0
	v_mov_b32_e32 v18, v0
	v_mov_b32_e32 v19, v0
	v_mov_b32_e32 v24, v0
	v_mov_b32_e32 v25, v0
	v_mov_b32_e32 v26, v0
	v_mov_b32_e32 v27, v0
	v_mov_b32_e32 v32, v0
	v_mov_b32_e32 v33, v0
	v_mov_b32_e32 v34, v0
	v_mov_b32_e32 v35, v0
	v_mov_b32_e32 v40, v0
	v_mov_b32_e32 v41, v0
	v_mov_b32_e32 v42, v0
	v_mov_b32_e32 v43, v0
	v_mov_b32_e32 v48, v0
	v_mov_b32_e32 v49, v0
	v_mov_b32_e32 v50, v0
	v_mov_b32_e32 v51, v0
	v_mov_b32_e32 v12, v0
	v_mov_b32_e32 v13, v0
	v_mov_b32_e32 v14, v0
	v_mov_b32_e32 v15, v0
	v_mov_b32_e32 v20, v0
	v_mov_b32_e32 v21, v0
	v_mov_b32_e32 v22, v0
	v_mov_b32_e32 v23, v0
	v_mov_b32_e32 v28, v0
	v_mov_b32_e32 v29, v0
	v_mov_b32_e32 v30, v0
	v_mov_b32_e32 v31, v0
	v_mov_b32_e32 v36, v0
	v_mov_b32_e32 v37, v0
	v_mov_b32_e32 v38, v0
	v_mov_b32_e32 v39, v0
	v_mov_b32_e32 v44, v0
	v_mov_b32_e32 v45, v0
	v_mov_b32_e32 v46, v0
	v_mov_b32_e32 v47, v0
	v_mov_b32_e32 v52, v0
	v_mov_b32_e32 v53, v0
	v_mov_b32_e32 v54, v0
	v_mov_b32_e32 v55, v0
	v_mov_b32_e32 v56, v0
	v_mov_b32_e32 v57, v0
	v_mov_b32_e32 v58, v0
	v_mov_b32_e32 v59, v0
	v_mov_b32_e32 v60, v0
	v_mov_b32_e32 v61, v0
	v_mov_b32_e32 v62, v0
	v_mov_b32_e32 v63, v0
	v_mov_b32_e32 v64, v0
	v_mov_b32_e32 v65, v0
	v_mov_b32_e32 v66, v0
	v_mov_b32_e32 v67, v0
	v_mov_b32_e32 v68, v0
	v_mov_b32_e32 v69, v0
	v_mov_b32_e32 v70, v0
	v_mov_b32_e32 v71, v0
	v_mov_b32_e32 v72, v0
	v_mov_b32_e32 v73, v0
	v_mov_b32_e32 v74, v0
	v_mov_b32_e32 v75, v0
	v_mov_b32_e32 v80, v0
	v_mov_b32_e32 v81, v0
	v_mov_b32_e32 v82, v0
	v_mov_b32_e32 v83, v0
	v_mov_b32_e32 v88, v0
	v_mov_b32_e32 v89, v0
	v_mov_b32_e32 v90, v0
	v_mov_b32_e32 v91, v0
	v_mov_b32_e32 v96, v0
	v_mov_b32_e32 v97, v0
	v_mov_b32_e32 v98, v0
	v_mov_b32_e32 v99, v0
	v_mov_b32_e32 v104, v0
	v_mov_b32_e32 v105, v0
	v_mov_b32_e32 v106, v0
	v_mov_b32_e32 v107, v0
	v_mov_b32_e32 v112, v0
	v_mov_b32_e32 v113, v0
	v_mov_b32_e32 v114, v0
	v_mov_b32_e32 v115, v0
	v_mov_b32_e32 v76, v0
	v_mov_b32_e32 v77, v0
	v_mov_b32_e32 v78, v0
	v_mov_b32_e32 v79, v0
	v_mov_b32_e32 v84, v0
	v_mov_b32_e32 v85, v0
	v_mov_b32_e32 v86, v0
	v_mov_b32_e32 v87, v0
	v_mov_b32_e32 v92, v0
	v_mov_b32_e32 v93, v0
	v_mov_b32_e32 v94, v0
	v_mov_b32_e32 v95, v0
	v_mov_b32_e32 v100, v0
	v_mov_b32_e32 v101, v0
	v_mov_b32_e32 v102, v0
	v_mov_b32_e32 v103, v0
	v_mov_b32_e32 v108, v0
	v_mov_b32_e32 v109, v0
	v_mov_b32_e32 v110, v0
	v_mov_b32_e32 v111, v0
	v_mov_b32_e32 v116, v0
	v_mov_b32_e32 v117, v0
	v_mov_b32_e32 v118, v0
	v_mov_b32_e32 v119, v0
	v_mov_b32_e32 v120, v0
	v_mov_b32_e32 v121, v0
	v_mov_b32_e32 v122, v0
	v_mov_b32_e32 v123, v0
	v_mov_b32_e32 v124, v0
	v_mov_b32_e32 v125, v0
	v_mov_b32_e32 v126, v0
	v_mov_b32_e32 v127, v0
	.p2align	6

.LBB0_757:
	s_ashr_i32 s35, s34, 31
	s_lshl_b64 s[36:37], s[34:35], 18
	v_readlane_b32 s38, v252, 20
	v_readlane_b32 s39, v252, 21
	s_add_u32 s38, s38, s36
	s_addc_u32 s39, s39, s37
	s_and_b64 s[36:37], s[0:1], exec
	s_cselect_b32 s35, s39, s43
	s_cselect_b32 s36, s38, s42
	s_ashr_i32 s31, s30, 31
	s_lshl_b64 s[40:41], s[30:31], 18
	s_add_u32 s40, s29, s40
	s_addc_u32 s41, s33, s41
	s_and_b64 s[46:47], s[0:1], exec
	s_cselect_b32 s31, s41, s45
	s_cselect_b32 s37, s40, s44
	s_add_u32 s42, s42, 0x20080
	s_addc_u32 s43, s43, 0
	s_add_u32 s48, s44, 0x100
	v_mov_b32_e32 v0, 0
	s_addc_u32 s49, s45, 0
	s_mov_b32 s50, -2
	v_mov_b32_e32 v1, v0
	v_mov_b32_e32 v2, v0
	v_mov_b32_e32 v3, v0
	v_mov_b32_e32 v4, v0
	v_mov_b32_e32 v5, v0
	v_mov_b32_e32 v6, v0
	v_mov_b32_e32 v7, v0
	v_mov_b32_e32 v8, v0
	v_mov_b32_e32 v9, v0
	v_mov_b32_e32 v10, v0
	v_mov_b32_e32 v11, v0
	v_mov_b32_e32 v12, v0
	v_mov_b32_e32 v13, v0
	v_mov_b32_e32 v14, v0
	v_mov_b32_e32 v15, v0
	v_mov_b32_e32 v24, v0
	v_mov_b32_e32 v25, v0
	v_mov_b32_e32 v26, v0
	v_mov_b32_e32 v27, v0
	v_mov_b32_e32 v28, v0
	v_mov_b32_e32 v29, v0
	v_mov_b32_e32 v30, v0
	v_mov_b32_e32 v31, v0
	v_mov_b32_e32 v40, v0
	v_mov_b32_e32 v41, v0
	v_mov_b32_e32 v42, v0
	v_mov_b32_e32 v43, v0
	v_mov_b32_e32 v44, v0
	v_mov_b32_e32 v45, v0
	v_mov_b32_e32 v46, v0
	v_mov_b32_e32 v47, v0
	v_mov_b32_e32 v16, v0
	v_mov_b32_e32 v17, v0
	v_mov_b32_e32 v18, v0
	v_mov_b32_e32 v19, v0
	v_mov_b32_e32 v20, v0
	v_mov_b32_e32 v21, v0
	v_mov_b32_e32 v22, v0
	v_mov_b32_e32 v23, v0
	v_mov_b32_e32 v32, v0
	v_mov_b32_e32 v33, v0
	v_mov_b32_e32 v34, v0
	v_mov_b32_e32 v35, v0
	v_mov_b32_e32 v36, v0
	v_mov_b32_e32 v37, v0
	v_mov_b32_e32 v38, v0
	v_mov_b32_e32 v39, v0
	v_mov_b32_e32 v48, v0
	v_mov_b32_e32 v49, v0
	v_mov_b32_e32 v50, v0
	v_mov_b32_e32 v51, v0
	v_mov_b32_e32 v52, v0
	v_mov_b32_e32 v53, v0
	v_mov_b32_e32 v54, v0
	v_mov_b32_e32 v55, v0
	v_mov_b32_e32 v56, v0
	v_mov_b32_e32 v57, v0
	v_mov_b32_e32 v58, v0
	v_mov_b32_e32 v59, v0
	v_mov_b32_e32 v60, v0
	v_mov_b32_e32 v61, v0
	v_mov_b32_e32 v62, v0
	v_mov_b32_e32 v63, v0
	v_mov_b32_e32 v64, v0
	v_mov_b32_e32 v65, v0
	v_mov_b32_e32 v66, v0
	v_mov_b32_e32 v67, v0
	v_mov_b32_e32 v68, v0
	v_mov_b32_e32 v69, v0
	v_mov_b32_e32 v70, v0
	v_mov_b32_e32 v71, v0
	v_mov_b32_e32 v72, v0
	v_mov_b32_e32 v73, v0
	v_mov_b32_e32 v74, v0
	v_mov_b32_e32 v75, v0
	v_mov_b32_e32 v76, v0
	v_mov_b32_e32 v77, v0
	v_mov_b32_e32 v78, v0
	v_mov_b32_e32 v79, v0
	v_mov_b32_e32 v88, v0
	v_mov_b32_e32 v89, v0
	v_mov_b32_e32 v90, v0
	v_mov_b32_e32 v91, v0
	v_mov_b32_e32 v92, v0
	v_mov_b32_e32 v93, v0
	v_mov_b32_e32 v94, v0
	v_mov_b32_e32 v95, v0
	v_mov_b32_e32 v104, v0
	v_mov_b32_e32 v105, v0
	v_mov_b32_e32 v106, v0
	v_mov_b32_e32 v107, v0
	v_mov_b32_e32 v108, v0
	v_mov_b32_e32 v109, v0
	v_mov_b32_e32 v110, v0
	v_mov_b32_e32 v111, v0
	v_mov_b32_e32 v80, v0
	v_mov_b32_e32 v81, v0
	v_mov_b32_e32 v82, v0
	v_mov_b32_e32 v83, v0
	v_mov_b32_e32 v84, v0
	v_mov_b32_e32 v85, v0
	v_mov_b32_e32 v86, v0
	v_mov_b32_e32 v87, v0
	v_mov_b32_e32 v96, v0
	v_mov_b32_e32 v97, v0
	v_mov_b32_e32 v98, v0
	v_mov_b32_e32 v99, v0
	v_mov_b32_e32 v100, v0
	v_mov_b32_e32 v101, v0
	v_mov_b32_e32 v102, v0
	v_mov_b32_e32 v103, v0
	v_mov_b32_e32 v112, v0
	v_mov_b32_e32 v113, v0
	v_mov_b32_e32 v114, v0
	v_mov_b32_e32 v115, v0
	v_mov_b32_e32 v116, v0
	v_mov_b32_e32 v117, v0
	v_mov_b32_e32 v118, v0
	v_mov_b32_e32 v119, v0
	v_mov_b32_e32 v120, v0
	v_mov_b32_e32 v121, v0
	v_mov_b32_e32 v122, v0
	v_mov_b32_e32 v123, v0
	v_mov_b32_e32 v124, v0
	v_mov_b32_e32 v125, v0
	v_mov_b32_e32 v126, v0
	v_mov_b32_e32 v127, v0
	.p2align	6

.LBB0_777:
	s_ashr_i32 s15, s14, 31
	s_lshl_b64 s[30:31], s[14:15], 18
	s_add_u32 s30, s29, s30
	s_addc_u32 s31, s33, s31
	s_and_b64 s[34:35], s[0:1], exec
	s_cselect_b32 s15, s31, s41
	s_cselect_b32 s46, s30, s40
	s_ashr_i32 s9, s8, 31
	s_lshl_b64 s[34:35], s[8:9], 18
	v_readlane_b32 s44, v252, 20
	v_readlane_b32 s45, v252, 21
	s_add_u32 s34, s44, s34
	s_addc_u32 s35, s45, s35
	s_and_b64 s[44:45], s[0:1], exec
	s_cselect_b32 s9, s35, s43
	s_cselect_b32 s47, s34, s42
	s_add_u32 s40, s40, 0x20080
	s_addc_u32 s41, s41, 0
	s_add_u32 s50, s42, 0x100
	v_mov_b32_e32 v0, 0
	s_addc_u32 s51, s43, 0
	s_mov_b32 s61, -2
	v_mov_b32_e32 v1, v0
	v_mov_b32_e32 v2, v0
	v_mov_b32_e32 v3, v0
	v_mov_b32_e32 v20, v0
	v_mov_b32_e32 v21, v0
	v_mov_b32_e32 v22, v0
	v_mov_b32_e32 v23, v0
	v_mov_b32_e32 v4, v0
	v_mov_b32_e32 v5, v0
	v_mov_b32_e32 v6, v0
	v_mov_b32_e32 v7, v0
	v_mov_b32_e32 v28, v0
	v_mov_b32_e32 v29, v0
	v_mov_b32_e32 v30, v0
	v_mov_b32_e32 v31, v0
	v_mov_b32_e32 v8, v0
	v_mov_b32_e32 v9, v0
	v_mov_b32_e32 v10, v0
	v_mov_b32_e32 v11, v0
	v_mov_b32_e32 v36, v0
	v_mov_b32_e32 v37, v0
	v_mov_b32_e32 v38, v0
	v_mov_b32_e32 v39, v0
	v_mov_b32_e32 v12, v0
	v_mov_b32_e32 v13, v0
	v_mov_b32_e32 v14, v0
	v_mov_b32_e32 v15, v0
	v_mov_b32_e32 v44, v0
	v_mov_b32_e32 v45, v0
	v_mov_b32_e32 v46, v0
	v_mov_b32_e32 v47, v0
	v_mov_b32_e32 v60, v0
	v_mov_b32_e32 v61, v0
	v_mov_b32_e32 v62, v0
	v_mov_b32_e32 v63, v0
	v_mov_b32_e32 v84, v0
	v_mov_b32_e32 v85, v0
	v_mov_b32_e32 v86, v0
	v_mov_b32_e32 v87, v0
	v_mov_b32_e32 v68, v0
	v_mov_b32_e32 v69, v0
	v_mov_b32_e32 v70, v0
	v_mov_b32_e32 v71, v0
	v_mov_b32_e32 v92, v0
	v_mov_b32_e32 v93, v0
	v_mov_b32_e32 v94, v0
	v_mov_b32_e32 v95, v0
	v_mov_b32_e32 v72, v0
	v_mov_b32_e32 v73, v0
	v_mov_b32_e32 v74, v0
	v_mov_b32_e32 v75, v0
	v_mov_b32_e32 v100, v0
	v_mov_b32_e32 v101, v0
	v_mov_b32_e32 v102, v0
	v_mov_b32_e32 v103, v0
	v_mov_b32_e32 v76, v0
	v_mov_b32_e32 v77, v0
	v_mov_b32_e32 v78, v0
	v_mov_b32_e32 v79, v0
	v_mov_b32_e32 v108, v0
	v_mov_b32_e32 v109, v0
	v_mov_b32_e32 v110, v0
	v_mov_b32_e32 v111, v0
	v_mov_b32_e32 v16, v0
	v_mov_b32_e32 v17, v0
	v_mov_b32_e32 v18, v0
	v_mov_b32_e32 v19, v0
	v_mov_b32_e32 v48, v0
	v_mov_b32_e32 v49, v0
	v_mov_b32_e32 v50, v0
	v_mov_b32_e32 v51, v0
	v_mov_b32_e32 v24, v0
	v_mov_b32_e32 v25, v0
	v_mov_b32_e32 v26, v0
	v_mov_b32_e32 v27, v0
	v_mov_b32_e32 v52, v0
	v_mov_b32_e32 v53, v0
	v_mov_b32_e32 v54, v0
	v_mov_b32_e32 v55, v0
	v_mov_b32_e32 v32, v0
	v_mov_b32_e32 v33, v0
	v_mov_b32_e32 v34, v0
	v_mov_b32_e32 v35, v0
	v_mov_b32_e32 v56, v0
	v_mov_b32_e32 v57, v0
	v_mov_b32_e32 v58, v0
	v_mov_b32_e32 v59, v0
	v_mov_b32_e32 v40, v0
	v_mov_b32_e32 v41, v0
	v_mov_b32_e32 v42, v0
	v_mov_b32_e32 v43, v0
	v_mov_b32_e32 v64, v0
	v_mov_b32_e32 v65, v0
	v_mov_b32_e32 v66, v0
	v_mov_b32_e32 v67, v0
	v_mov_b32_e32 v80, v0
	v_mov_b32_e32 v81, v0
	v_mov_b32_e32 v82, v0
	v_mov_b32_e32 v83, v0
	v_mov_b32_e32 v112, v0
	v_mov_b32_e32 v113, v0
	v_mov_b32_e32 v114, v0
	v_mov_b32_e32 v115, v0
	v_mov_b32_e32 v88, v0
	v_mov_b32_e32 v89, v0
	v_mov_b32_e32 v90, v0
	v_mov_b32_e32 v91, v0
	v_mov_b32_e32 v116, v0
	v_mov_b32_e32 v117, v0
	v_mov_b32_e32 v118, v0
	v_mov_b32_e32 v119, v0
	v_mov_b32_e32 v96, v0
	v_mov_b32_e32 v97, v0
	v_mov_b32_e32 v98, v0
	v_mov_b32_e32 v99, v0
	v_mov_b32_e32 v120, v0
	v_mov_b32_e32 v121, v0
	v_mov_b32_e32 v122, v0
	v_mov_b32_e32 v123, v0
	v_mov_b32_e32 v104, v0
	v_mov_b32_e32 v105, v0
	v_mov_b32_e32 v106, v0
	v_mov_b32_e32 v107, v0
	v_mov_b32_e32 v124, v0
	v_mov_b32_e32 v125, v0
	v_mov_b32_e32 v126, v0
	v_mov_b32_e32 v127, v0
	.p2align	6

.LBB0_1140:
	s_add_i32 s35, s48, -2
	s_add_u32 s52, s52, 0x100080
	s_addc_u32 s53, s53, 0
	s_add_u32 s37, s54, 0x100
	v_mov_b32_e32 v0, 0
	s_addc_u32 s39, s55, 0
	s_mov_b32 s45, 0
	v_mov_b32_e32 v1, v0
	v_mov_b32_e32 v2, v0
	v_mov_b32_e32 v3, v0
	v_mov_b32_e32 v4, v0
	v_mov_b32_e32 v5, v0
	v_mov_b32_e32 v6, v0
	v_mov_b32_e32 v7, v0
	v_mov_b32_e32 v16, v0
	v_mov_b32_e32 v17, v0
	v_mov_b32_e32 v18, v0
	v_mov_b32_e32 v19, v0
	v_mov_b32_e32 v20, v0
	v_mov_b32_e32 v21, v0
	v_mov_b32_e32 v22, v0
	v_mov_b32_e32 v23, v0
	v_mov_b32_e32 v32, v0
	v_mov_b32_e32 v33, v0
	v_mov_b32_e32 v34, v0
	v_mov_b32_e32 v35, v0
	v_mov_b32_e32 v36, v0
	v_mov_b32_e32 v37, v0
	v_mov_b32_e32 v38, v0
	v_mov_b32_e32 v39, v0
	v_mov_b32_e32 v48, v0
	v_mov_b32_e32 v49, v0
	v_mov_b32_e32 v50, v0
	v_mov_b32_e32 v51, v0
	v_mov_b32_e32 v52, v0
	v_mov_b32_e32 v53, v0
	v_mov_b32_e32 v54, v0
	v_mov_b32_e32 v55, v0
	v_mov_b32_e32 v8, v0
	v_mov_b32_e32 v9, v0
	v_mov_b32_e32 v10, v0
	v_mov_b32_e32 v11, v0
	v_mov_b32_e32 v12, v0
	v_mov_b32_e32 v13, v0
	v_mov_b32_e32 v14, v0
	v_mov_b32_e32 v15, v0
	v_mov_b32_e32 v24, v0
	v_mov_b32_e32 v25, v0
	v_mov_b32_e32 v26, v0
	v_mov_b32_e32 v27, v0
	v_mov_b32_e32 v28, v0
	v_mov_b32_e32 v29, v0
	v_mov_b32_e32 v30, v0
	v_mov_b32_e32 v31, v0
	v_mov_b32_e32 v40, v0
	v_mov_b32_e32 v41, v0
	v_mov_b32_e32 v42, v0
	v_mov_b32_e32 v43, v0
	v_mov_b32_e32 v44, v0
	v_mov_b32_e32 v45, v0
	v_mov_b32_e32 v46, v0
	v_mov_b32_e32 v47, v0
	v_mov_b32_e32 v56, v0
	v_mov_b32_e32 v57, v0
	v_mov_b32_e32 v58, v0
	v_mov_b32_e32 v59, v0
	v_mov_b32_e32 v60, v0
	v_mov_b32_e32 v61, v0
	v_mov_b32_e32 v62, v0
	v_mov_b32_e32 v63, v0
	v_mov_b32_e32 v64, v0
	v_mov_b32_e32 v65, v0
	v_mov_b32_e32 v66, v0
	v_mov_b32_e32 v67, v0
	v_mov_b32_e32 v68, v0
	v_mov_b32_e32 v69, v0
	v_mov_b32_e32 v70, v0
	v_mov_b32_e32 v71, v0
	v_mov_b32_e32 v80, v0
	v_mov_b32_e32 v81, v0
	v_mov_b32_e32 v82, v0
	v_mov_b32_e32 v83, v0
	v_mov_b32_e32 v84, v0
	v_mov_b32_e32 v85, v0
	v_mov_b32_e32 v86, v0
	v_mov_b32_e32 v87, v0
	v_mov_b32_e32 v96, v0
	v_mov_b32_e32 v97, v0
	v_mov_b32_e32 v98, v0
	v_mov_b32_e32 v99, v0
	v_mov_b32_e32 v100, v0
	v_mov_b32_e32 v101, v0
	v_mov_b32_e32 v102, v0
	v_mov_b32_e32 v103, v0
	v_mov_b32_e32 v112, v0
	v_mov_b32_e32 v113, v0
	v_mov_b32_e32 v114, v0
	v_mov_b32_e32 v115, v0
	v_mov_b32_e32 v116, v0
	v_mov_b32_e32 v117, v0
	v_mov_b32_e32 v118, v0
	v_mov_b32_e32 v119, v0
	v_mov_b32_e32 v72, v0
	v_mov_b32_e32 v73, v0
	v_mov_b32_e32 v74, v0
	v_mov_b32_e32 v75, v0
	v_mov_b32_e32 v76, v0
	v_mov_b32_e32 v77, v0
	v_mov_b32_e32 v78, v0
	v_mov_b32_e32 v79, v0
	v_mov_b32_e32 v88, v0
	v_mov_b32_e32 v89, v0
	v_mov_b32_e32 v90, v0
	v_mov_b32_e32 v91, v0
	v_mov_b32_e32 v92, v0
	v_mov_b32_e32 v93, v0
	v_mov_b32_e32 v94, v0
	v_mov_b32_e32 v95, v0
	v_mov_b32_e32 v104, v0
	v_mov_b32_e32 v105, v0
	v_mov_b32_e32 v106, v0
	v_mov_b32_e32 v107, v0
	v_mov_b32_e32 v108, v0
	v_mov_b32_e32 v109, v0
	v_mov_b32_e32 v110, v0
	v_mov_b32_e32 v111, v0
	v_mov_b32_e32 v120, v0
	v_mov_b32_e32 v121, v0
	v_mov_b32_e32 v122, v0
	v_mov_b32_e32 v123, v0
	v_mov_b32_e32 v124, v0
	v_mov_b32_e32 v125, v0
	v_mov_b32_e32 v126, v0
	v_mov_b32_e32 v127, v0
	.p2align	6

.LBB0_1298:
	s_ashr_i32 s13, s12, 31
	s_lshl_b64 s[14:15], s[12:13], 21
	v_readlane_b32 s16, v253, 6
	v_readlane_b32 s17, v253, 7
	s_add_u32 s14, s16, s14
	s_addc_u32 s15, s17, s15
	s_and_b64 s[16:17], s[0:1], exec
	s_cselect_b32 s13, s15, s35
	s_cselect_b32 s53, s14, s34
	s_ashr_i32 s11, s10, 31
	s_lshl_b64 s[16:17], s[10:11], 21
	s_add_u32 s16, s40, s16
	s_addc_u32 s17, s41, s17
	s_and_b64 s[38:39], s[0:1], exec
	s_cselect_b32 s11, s17, s37
	s_cselect_b32 s54, s16, s36
	s_add_u32 s34, s34, 0x100080
	s_addc_u32 s35, s35, 0
	s_add_u32 s55, s36, 0x100
	v_mov_b32_e32 v0, 0
	s_addc_u32 s56, s37, 0
	s_mov_b32 s57, -2
	v_mov_b32_e32 v1, v0
	v_mov_b32_e32 v2, v0
	v_mov_b32_e32 v3, v0
	v_mov_b32_e32 v4, v0
	v_mov_b32_e32 v5, v0
	v_mov_b32_e32 v6, v0
	v_mov_b32_e32 v7, v0
	v_mov_b32_e32 v16, v0
	v_mov_b32_e32 v17, v0
	v_mov_b32_e32 v18, v0
	v_mov_b32_e32 v19, v0
	v_mov_b32_e32 v20, v0
	v_mov_b32_e32 v21, v0
	v_mov_b32_e32 v22, v0
	v_mov_b32_e32 v23, v0
	v_mov_b32_e32 v32, v0
	v_mov_b32_e32 v33, v0
	v_mov_b32_e32 v34, v0
	v_mov_b32_e32 v35, v0
	v_mov_b32_e32 v36, v0
	v_mov_b32_e32 v37, v0
	v_mov_b32_e32 v38, v0
	v_mov_b32_e32 v39, v0
	v_mov_b32_e32 v48, v0
	v_mov_b32_e32 v49, v0
	v_mov_b32_e32 v50, v0
	v_mov_b32_e32 v51, v0
	v_mov_b32_e32 v52, v0
	v_mov_b32_e32 v53, v0
	v_mov_b32_e32 v54, v0
	v_mov_b32_e32 v55, v0
	v_mov_b32_e32 v8, v0
	v_mov_b32_e32 v9, v0
	v_mov_b32_e32 v10, v0
	v_mov_b32_e32 v11, v0
	v_mov_b32_e32 v12, v0
	v_mov_b32_e32 v13, v0
	v_mov_b32_e32 v14, v0
	v_mov_b32_e32 v15, v0
	v_mov_b32_e32 v24, v0
	v_mov_b32_e32 v25, v0
	v_mov_b32_e32 v26, v0
	v_mov_b32_e32 v27, v0
	v_mov_b32_e32 v28, v0
	v_mov_b32_e32 v29, v0
	v_mov_b32_e32 v30, v0
	v_mov_b32_e32 v31, v0
	v_mov_b32_e32 v40, v0
	v_mov_b32_e32 v41, v0
	v_mov_b32_e32 v42, v0
	v_mov_b32_e32 v43, v0
	v_mov_b32_e32 v44, v0
	v_mov_b32_e32 v45, v0
	v_mov_b32_e32 v46, v0
	v_mov_b32_e32 v47, v0
	v_mov_b32_e32 v56, v0
	v_mov_b32_e32 v57, v0
	v_mov_b32_e32 v58, v0
	v_mov_b32_e32 v59, v0
	v_mov_b32_e32 v60, v0
	v_mov_b32_e32 v61, v0
	v_mov_b32_e32 v62, v0
	v_mov_b32_e32 v63, v0
	v_mov_b32_e32 v64, v0
	v_mov_b32_e32 v65, v0
	v_mov_b32_e32 v66, v0
	v_mov_b32_e32 v67, v0
	v_mov_b32_e32 v68, v0
	v_mov_b32_e32 v69, v0
	v_mov_b32_e32 v70, v0
	v_mov_b32_e32 v71, v0
	v_mov_b32_e32 v80, v0
	v_mov_b32_e32 v81, v0
	v_mov_b32_e32 v82, v0
	v_mov_b32_e32 v83, v0
	v_mov_b32_e32 v84, v0
	v_mov_b32_e32 v85, v0
	v_mov_b32_e32 v86, v0
	v_mov_b32_e32 v87, v0
	v_mov_b32_e32 v96, v0
	v_mov_b32_e32 v97, v0
	v_mov_b32_e32 v98, v0
	v_mov_b32_e32 v99, v0
	v_mov_b32_e32 v100, v0
	v_mov_b32_e32 v101, v0
	v_mov_b32_e32 v102, v0
	v_mov_b32_e32 v103, v0
	v_mov_b32_e32 v112, v0
	v_mov_b32_e32 v113, v0
	v_mov_b32_e32 v114, v0
	v_mov_b32_e32 v115, v0
	v_mov_b32_e32 v116, v0
	v_mov_b32_e32 v117, v0
	v_mov_b32_e32 v118, v0
	v_mov_b32_e32 v119, v0
	v_mov_b32_e32 v72, v0
	v_mov_b32_e32 v73, v0
	v_mov_b32_e32 v74, v0
	v_mov_b32_e32 v75, v0
	v_mov_b32_e32 v76, v0
	v_mov_b32_e32 v77, v0
	v_mov_b32_e32 v78, v0
	v_mov_b32_e32 v79, v0
	v_mov_b32_e32 v88, v0
	v_mov_b32_e32 v89, v0
	v_mov_b32_e32 v90, v0
	v_mov_b32_e32 v91, v0
	v_mov_b32_e32 v92, v0
	v_mov_b32_e32 v93, v0
	v_mov_b32_e32 v94, v0
	v_mov_b32_e32 v95, v0
	v_mov_b32_e32 v104, v0
	v_mov_b32_e32 v105, v0
	v_mov_b32_e32 v106, v0
	v_mov_b32_e32 v107, v0
	v_mov_b32_e32 v108, v0
	v_mov_b32_e32 v109, v0
	v_mov_b32_e32 v110, v0
	v_mov_b32_e32 v111, v0
	v_mov_b32_e32 v120, v0
	v_mov_b32_e32 v121, v0
	v_mov_b32_e32 v122, v0
	v_mov_b32_e32 v123, v0
	v_mov_b32_e32 v124, v0
	v_mov_b32_e32 v125, v0
	v_mov_b32_e32 v126, v0
	v_mov_b32_e32 v127, v0
	.p2align	6

.LBB0_1408:
	s_add_i32 s37, s67, -2
	s_add_u32 s68, s44, 0x100
	v_mov_b32_e32 v0, 0
	s_addc_u32 s69, s45, 0
	s_mov_b32 s46, 0
	v_mov_b32_e32 v1, v0
	v_mov_b32_e32 v2, v0
	v_mov_b32_e32 v3, v0
	v_mov_b32_e32 v4, v0
	v_mov_b32_e32 v5, v0
	v_mov_b32_e32 v6, v0
	v_mov_b32_e32 v7, v0
	v_mov_b32_e32 v16, v0
	v_mov_b32_e32 v17, v0
	v_mov_b32_e32 v18, v0
	v_mov_b32_e32 v19, v0
	v_mov_b32_e32 v20, v0
	v_mov_b32_e32 v21, v0
	v_mov_b32_e32 v22, v0
	v_mov_b32_e32 v23, v0
	v_mov_b32_e32 v32, v0
	v_mov_b32_e32 v33, v0
	v_mov_b32_e32 v34, v0
	v_mov_b32_e32 v35, v0
	v_mov_b32_e32 v36, v0
	v_mov_b32_e32 v37, v0
	v_mov_b32_e32 v38, v0
	v_mov_b32_e32 v39, v0
	v_mov_b32_e32 v48, v0
	v_mov_b32_e32 v49, v0
	v_mov_b32_e32 v50, v0
	v_mov_b32_e32 v51, v0
	v_mov_b32_e32 v52, v0
	v_mov_b32_e32 v53, v0
	v_mov_b32_e32 v54, v0
	v_mov_b32_e32 v55, v0
	v_mov_b32_e32 v8, v0
	v_mov_b32_e32 v9, v0
	v_mov_b32_e32 v10, v0
	v_mov_b32_e32 v11, v0
	v_mov_b32_e32 v12, v0
	v_mov_b32_e32 v13, v0
	v_mov_b32_e32 v14, v0
	v_mov_b32_e32 v15, v0
	v_mov_b32_e32 v24, v0
	v_mov_b32_e32 v25, v0
	v_mov_b32_e32 v26, v0
	v_mov_b32_e32 v27, v0
	v_mov_b32_e32 v28, v0
	v_mov_b32_e32 v29, v0
	v_mov_b32_e32 v30, v0
	v_mov_b32_e32 v31, v0
	v_mov_b32_e32 v40, v0
	v_mov_b32_e32 v41, v0
	v_mov_b32_e32 v42, v0
	v_mov_b32_e32 v43, v0
	v_mov_b32_e32 v44, v0
	v_mov_b32_e32 v45, v0
	v_mov_b32_e32 v46, v0
	v_mov_b32_e32 v47, v0
	v_mov_b32_e32 v56, v0
	v_mov_b32_e32 v57, v0
	v_mov_b32_e32 v58, v0
	v_mov_b32_e32 v59, v0
	v_mov_b32_e32 v60, v0
	v_mov_b32_e32 v61, v0
	v_mov_b32_e32 v62, v0
	v_mov_b32_e32 v63, v0
	v_mov_b32_e32 v64, v0
	v_mov_b32_e32 v65, v0
	v_mov_b32_e32 v66, v0
	v_mov_b32_e32 v67, v0
	v_mov_b32_e32 v68, v0
	v_mov_b32_e32 v69, v0
	v_mov_b32_e32 v70, v0
	v_mov_b32_e32 v71, v0
	v_mov_b32_e32 v80, v0
	v_mov_b32_e32 v81, v0
	v_mov_b32_e32 v82, v0
	v_mov_b32_e32 v83, v0
	v_mov_b32_e32 v84, v0
	v_mov_b32_e32 v85, v0
	v_mov_b32_e32 v86, v0
	v_mov_b32_e32 v87, v0
	v_mov_b32_e32 v96, v0
	v_mov_b32_e32 v97, v0
	v_mov_b32_e32 v98, v0
	v_mov_b32_e32 v99, v0
	v_mov_b32_e32 v100, v0
	v_mov_b32_e32 v101, v0
	v_mov_b32_e32 v102, v0
	v_mov_b32_e32 v103, v0
	v_mov_b32_e32 v112, v0
	v_mov_b32_e32 v113, v0
	v_mov_b32_e32 v114, v0
	v_mov_b32_e32 v115, v0
	v_mov_b32_e32 v116, v0
	v_mov_b32_e32 v117, v0
	v_mov_b32_e32 v118, v0
	v_mov_b32_e32 v119, v0
	v_mov_b32_e32 v72, v0
	v_mov_b32_e32 v73, v0
	v_mov_b32_e32 v74, v0
	v_mov_b32_e32 v75, v0
	v_mov_b32_e32 v76, v0
	v_mov_b32_e32 v77, v0
	v_mov_b32_e32 v78, v0
	v_mov_b32_e32 v79, v0
	v_mov_b32_e32 v88, v0
	v_mov_b32_e32 v89, v0
	v_mov_b32_e32 v90, v0
	v_mov_b32_e32 v91, v0
	v_mov_b32_e32 v92, v0
	v_mov_b32_e32 v93, v0
	v_mov_b32_e32 v94, v0
	v_mov_b32_e32 v95, v0
	v_mov_b32_e32 v104, v0
	v_mov_b32_e32 v105, v0
	v_mov_b32_e32 v106, v0
	v_mov_b32_e32 v107, v0
	v_mov_b32_e32 v108, v0
	v_mov_b32_e32 v109, v0
	v_mov_b32_e32 v110, v0
	v_mov_b32_e32 v111, v0
	v_mov_b32_e32 v120, v0
	v_mov_b32_e32 v121, v0
	v_mov_b32_e32 v122, v0
	v_mov_b32_e32 v123, v0
	v_mov_b32_e32 v124, v0
	v_mov_b32_e32 v125, v0
	v_mov_b32_e32 v126, v0
	v_mov_b32_e32 v127, v0
	.p2align	6
